# hgrn_c unit: 32 serialized 2-byte loads issued up front (on top of fast top-k selection)
# speedup vs baseline: 1.0805x; 1.0212x over previous
.LBB0_130:
	s_ashr_i32 s14, s12, 8
	s_lshl_b32 s13, s12, 6
	v_ashrrev_i32_e32 v29, 6, v32
	s_lshl_b32 s5, s14, 12
	s_and_b32 s26, s13, 0xfc0
	s_or_b32 s5, s5, s26
	v_lshlrev_b32_e32 v6, 4, v29
	v_add_u32_e32 v0, s5, v6
	v_mov_b64_e32 v[2:3], s[92:93]
	v_mad_i64_i32 v[2:3], s[16:17], v0, s63, v[2:3]
	s_lshl_b32 s84, s4, 1
	v_lshl_add_u64 v[2:3], v[2:3], 0, s[84:85]
	v_lshlrev_b32_e32 v152, 1, v7
	v_lshl_add_u64 v[4:5], v[2:3], 0, v[152:153]
	s_mul_i32 s30, s5, 0x1800
	s_add_u32 s28, s92, s30
	s_addc_u32 s29, s93, 0
	s_add_u32 s28, s28, s84
	s_addc_u32 s29, s29, 0
	v_mul_u32_u24_e32 v113, 0x1800, v6
	v_add_u32_e32 v112, v113, v152
	global_load_ushort v80, v112, s[28:29]
	global_load_ushort v81, v112, s[28:29] offset:512
	s_add_u32 s28, s28, 0x1800
	s_addc_u32 s29, s29, 0
	global_load_ushort v82, v112, s[28:29]
	global_load_ushort v83, v112, s[28:29] offset:512
	s_add_u32 s28, s28, 0x1800
	s_addc_u32 s29, s29, 0
	global_load_ushort v84, v112, s[28:29]
	global_load_ushort v85, v112, s[28:29] offset:512
	s_add_u32 s28, s28, 0x1800
	s_addc_u32 s29, s29, 0
	global_load_ushort v86, v112, s[28:29]
	global_load_ushort v87, v112, s[28:29] offset:512
	s_add_u32 s28, s28, 0x1800
	s_addc_u32 s29, s29, 0
	global_load_ushort v88, v112, s[28:29]
	global_load_ushort v89, v112, s[28:29] offset:512
	s_add_u32 s28, s28, 0x1800
	s_addc_u32 s29, s29, 0
	global_load_ushort v90, v112, s[28:29]
	global_load_ushort v91, v112, s[28:29] offset:512
	s_add_u32 s28, s28, 0x1800
	s_addc_u32 s29, s29, 0
	global_load_ushort v92, v112, s[28:29]
	global_load_ushort v93, v112, s[28:29] offset:512
	s_add_u32 s28, s28, 0x1800
	s_addc_u32 s29, s29, 0
	global_load_ushort v94, v112, s[28:29]
	global_load_ushort v95, v112, s[28:29] offset:512
	s_add_u32 s28, s28, 0x1800
	s_addc_u32 s29, s29, 0
	global_load_ushort v96, v112, s[28:29]
	global_load_ushort v97, v112, s[28:29] offset:512
	s_add_u32 s28, s28, 0x1800
	s_addc_u32 s29, s29, 0
	global_load_ushort v98, v112, s[28:29]
	global_load_ushort v99, v112, s[28:29] offset:512
	s_add_u32 s28, s28, 0x1800
	s_addc_u32 s29, s29, 0
	global_load_ushort v100, v112, s[28:29]
	global_load_ushort v101, v112, s[28:29] offset:512
	s_add_u32 s28, s28, 0x1800
	s_addc_u32 s29, s29, 0
	global_load_ushort v102, v112, s[28:29]
	global_load_ushort v103, v112, s[28:29] offset:512
	s_add_u32 s28, s28, 0x1800
	s_addc_u32 s29, s29, 0
	global_load_ushort v104, v112, s[28:29]
	global_load_ushort v105, v112, s[28:29] offset:512
	s_add_u32 s28, s28, 0x1800
	s_addc_u32 s29, s29, 0
	global_load_ushort v106, v112, s[28:29]
	global_load_ushort v107, v112, s[28:29] offset:512
	s_add_u32 s28, s28, 0x1800
	s_addc_u32 s29, s29, 0
	global_load_ushort v108, v112, s[28:29]
	global_load_ushort v109, v112, s[28:29] offset:512
	s_add_u32 s28, s28, 0x1800
	s_addc_u32 s29, s29, 0
	global_load_ushort v110, v112, s[28:29]
	global_load_ushort v111, v112, s[28:29] offset:512
	s_add_u32 s28, s28, 0x1800
	s_addc_u32 s29, s29, 0
	s_waitcnt vmcnt(0)
	v_mov_b32_e32 v2, v81
	v_sub_f32_e32 v9, 1.0, v24
	v_lshlrev_b32_e32 v0, 2, v7
	s_waitcnt vmcnt(0)
	v_lshlrev_b32_e32 v17, 16, v2
	v_mul_f32_e32 v2, 0xbfb8aa3b, v17
	v_exp_f32_e32 v2, v2
	s_nop 0
	v_add_f32_e32 v2, 1.0, v2
	v_div_scale_f32 v3, s[4:5], v2, v2, 1.0
	v_rcp_f32_e32 v8, v3
	s_nop 0
	v_fma_f32 v10, -v3, v8, 1.0
	v_fmac_f32_e32 v8, v10, v8
	v_div_scale_f32 v10, vcc, 1.0, v2, 1.0
	v_mul_f32_e32 v11, v10, v8
	v_fma_f32 v12, -v3, v11, v10
	v_fmac_f32_e32 v11, v12, v8
	v_fma_f32 v3, -v3, v11, v10
	v_div_fmas_f32 v3, v3, v8, v11
	v_div_fixup_f32 v2, v3, v2, 1.0
	v_fma_f32 v2, v9, v2, v24
	v_max_f32_e32 v2, 0xda24260, v2
	v_log_f32_e32 v2, v2
	v_mul_lo_u32 v8, v29, s80
	v_add_u32_e32 v3, v0, v8
	v_add_f32_e32 v10, 0, v2
	v_mov_b32_e32 v2, v80
	s_waitcnt vmcnt(0)
	v_lshlrev_b32_e32 v2, 16, v2
	v_mul_f32_e32 v2, 0x3e000000, v2
	ds_write_b32 v3, v2 offset:33280
	v_add_co_u32_e32 v2, vcc, s64, v4
	s_nop 1
	v_addc_co_u32_e32 v3, vcc, 0, v5, vcc
	v_mov_b32_e32 v11, v83
	s_waitcnt vmcnt(0)
	v_lshlrev_b32_e32 v18, 16, v11
	v_mov_b32_e32 v2, v82
	v_mul_f32_e32 v11, 0xbfb8aa3b, v18
	v_exp_f32_e32 v11, v11
	s_waitcnt vmcnt(0)
	v_lshlrev_b32_e32 v2, 16, v2
	v_add_f32_e32 v11, 1.0, v11
	v_div_scale_f32 v12, s[4:5], v11, v11, 1.0
	v_rcp_f32_e32 v13, v12
	s_nop 0
	v_fma_f32 v14, -v12, v13, 1.0
	v_fmac_f32_e32 v13, v14, v13
	v_div_scale_f32 v14, vcc, 1.0, v11, 1.0
	v_mul_f32_e32 v15, v14, v13
	v_fma_f32 v16, -v12, v15, v14
	v_fmac_f32_e32 v15, v16, v13
	v_fma_f32 v12, -v12, v15, v14
	v_div_fmas_f32 v12, v12, v13, v15
	v_div_fixup_f32 v11, v12, v11, 1.0
	v_or_b32_e32 v12, 1, v6
	v_mul_f32_e32 v13, 0x3e000000, v2
	v_mad_u64_u32 v[2:3], s[4:5], v12, s81, v[0:1]
	s_movk_i32 s4, 0x3000
	s_nop 0
	v_add_co_u32_e32 v14, vcc, s4, v4
	v_fma_f32 v11, v9, v11, v24
	s_nop 0
	v_addc_co_u32_e32 v15, vcc, 0, v5, vcc
	v_mov_b32_e32 v3, v85
	v_max_f32_e32 v11, 0xda24260, v11
	v_mov_b32_e32 v14, v84
	v_add_u32_e32 v15, 0x8000, v2
	v_log_f32_e32 v11, v11
	s_waitcnt vmcnt(1)
	v_lshlrev_b32_e32 v19, 16, v3
	v_mul_f32_e32 v3, 0xbfb8aa3b, v19
	v_exp_f32_e32 v3, v3
	s_waitcnt vmcnt(0)
	v_lshlrev_b32_e32 v14, 16, v14
	v_mul_f32_e32 v14, 0x3e000000, v14
	ds_write2_b32 v15, v13, v14 offset0:128 offset1:193
	v_add_f32_e32 v3, 1.0, v3
	v_div_scale_f32 v16, s[4:5], v3, v3, 1.0
	v_rcp_f32_e32 v20, v16
	v_add_f32_e32 v11, v10, v11
	v_fma_f32 v21, -v16, v20, 1.0
	v_fmac_f32_e32 v20, v21, v20
	v_div_scale_f32 v21, vcc, 1.0, v3, 1.0
	v_mul_f32_e32 v22, v21, v20
	v_fma_f32 v23, -v16, v22, v21
	v_fmac_f32_e32 v22, v23, v20
	v_fma_f32 v16, -v16, v22, v21
	v_div_fmas_f32 v16, v16, v20, v22
	v_add_co_u32_e32 v14, vcc, s74, v4
	v_div_fixup_f32 v3, v16, v3, 1.0
	s_nop 0
	v_addc_co_u32_e32 v15, vcc, 0, v5, vcc
	v_mov_b32_e32 v13, v87
	v_fma_f32 v3, v9, v3, v24
	v_mov_b32_e32 v14, v86
	v_max_f32_e32 v3, 0xda24260, v3
	v_log_f32_e32 v3, v3
	s_waitcnt vmcnt(1)
	v_lshlrev_b32_e32 v21, 16, v13
	v_mul_f32_e32 v13, 0xbfb8aa3b, v21
	v_exp_f32_e32 v13, v13
	s_waitcnt vmcnt(0)
	v_lshlrev_b32_e32 v14, 16, v14
	v_mul_f32_e32 v15, 0x3e000000, v14
	v_add_f32_e32 v3, v11, v3
	v_add_f32_e32 v13, 1.0, v13
	v_div_scale_f32 v16, s[4:5], v13, v13, 1.0
	v_rcp_f32_e32 v20, v16
	s_movk_i32 s4, 0x6000
	v_fma_f32 v22, -v16, v20, 1.0
	v_fmac_f32_e32 v20, v22, v20
	v_div_scale_f32 v22, vcc, 1.0, v13, 1.0
	v_mul_f32_e32 v23, v22, v20
	v_fma_f32 v25, -v16, v23, v22
	v_fmac_f32_e32 v23, v25, v20
	v_fma_f32 v16, -v16, v23, v22
	v_div_fmas_f32 v16, v16, v20, v23
	v_add_co_u32_e32 v26, vcc, s4, v4
	v_div_fixup_f32 v13, v16, v13, 1.0
	s_nop 0
	v_addc_co_u32_e32 v27, vcc, 0, v5, vcc
	v_mov_b32_e32 v14, v89
	v_fma_f32 v13, v9, v13, v24
	v_max_f32_e32 v13, 0xda24260, v13
	v_log_f32_e32 v13, v13
	s_waitcnt vmcnt(0)
	v_lshlrev_b32_e32 v22, 16, v14
	v_mul_f32_e32 v14, 0xbfb8aa3b, v22
	v_exp_f32_e32 v14, v14
	v_add_f32_e32 v13, v3, v13
	v_add_f32_e32 v14, 1.0, v14
	v_div_scale_f32 v16, s[4:5], v14, v14, 1.0
	v_rcp_f32_e32 v20, v16
	s_movk_i32 s4, 0x7000
	v_fma_f32 v23, -v16, v20, 1.0
	v_fmac_f32_e32 v20, v23, v20
	v_div_scale_f32 v23, vcc, 1.0, v14, 1.0
	v_mul_f32_e32 v25, v23, v20
	v_fma_f32 v28, -v16, v25, v23
	v_fmac_f32_e32 v25, v28, v20
	v_fma_f32 v16, -v16, v25, v23
	v_div_fmas_f32 v16, v16, v20, v25
	v_div_fixup_f32 v14, v16, v14, 1.0
	v_mov_b32_e32 v16, v88
	v_add_co_u32_e32 v26, vcc, s4, v4
	v_add_u32_e32 v20, 0x8400, v2
	s_nop 0
	v_addc_co_u32_e32 v27, vcc, 0, v5, vcc
	v_fma_f32 v14, v9, v14, v24
	v_max_f32_e32 v14, 0xda24260, v14
	v_log_f32_e32 v14, v14
	s_waitcnt vmcnt(0)
	v_lshlrev_b32_e32 v16, 16, v16
	v_mul_f32_e32 v16, 0x3e000000, v16
	ds_write2_b32 v20, v15, v16 offset0:2 offset1:67
	v_mov_b32_e32 v15, v91
	v_add_f32_e32 v14, v13, v14
	s_waitcnt vmcnt(0)
	v_lshlrev_b32_e32 v23, 16, v15
	v_mul_f32_e32 v15, 0xbfb8aa3b, v23
	v_exp_f32_e32 v15, v15
	s_nop 0
	v_add_f32_e32 v15, 1.0, v15
	v_div_scale_f32 v16, s[4:5], v15, v15, 1.0
	v_rcp_f32_e32 v25, v16
	s_mov_b32 s4, 0x9000
	v_fma_f32 v28, -v16, v25, 1.0
	v_fmac_f32_e32 v25, v28, v25
	v_div_scale_f32 v28, vcc, 1.0, v15, 1.0
	v_mul_f32_e32 v30, v28, v25
	v_fma_f32 v31, -v16, v30, v28
	v_fmac_f32_e32 v30, v31, v25
	v_fma_f32 v16, -v16, v30, v28
	v_div_fmas_f32 v16, v16, v25, v30
	v_div_fixup_f32 v15, v16, v15, 1.0
	v_mov_b32_e32 v16, v90
	v_add_co_u32_e32 v26, vcc, s4, v4
	v_fma_f32 v15, v9, v15, v24
	s_nop 0
	v_addc_co_u32_e32 v27, vcc, 0, v5, vcc
	v_max_f32_e32 v15, 0xda24260, v15
	v_log_f32_e32 v15, v15
	s_waitcnt vmcnt(0)
	v_lshlrev_b32_e32 v16, 16, v16
	v_mul_f32_e32 v28, 0x3e000000, v16
	v_mov_b32_e32 v16, v93
	v_add_f32_e32 v15, v14, v15
	v_mov_b32_e32 v26, v92
	s_waitcnt vmcnt(1)
	v_lshlrev_b32_e32 v25, 16, v16
	v_mul_f32_e32 v16, 0xbfb8aa3b, v25
	v_exp_f32_e32 v16, v16
	s_waitcnt vmcnt(0)
	v_lshlrev_b32_e32 v26, 16, v26
	v_mul_f32_e32 v26, 0x3e000000, v26
	ds_write2_b32 v20, v28, v26 offset0:132 offset1:197
	v_add_f32_e32 v16, 1.0, v16
	v_div_scale_f32 v30, s[4:5], v16, v16, 1.0
	v_rcp_f32_e32 v31, v30
	s_mov_b32 s4, 0xa000
	v_fma_f32 v33, -v30, v31, 1.0
	v_fmac_f32_e32 v31, v33, v31
	v_div_scale_f32 v33, vcc, 1.0, v16, 1.0
	v_mul_f32_e32 v34, v33, v31
	v_fma_f32 v35, -v30, v34, v33
	v_fmac_f32_e32 v34, v35, v31
	v_fma_f32 v30, -v30, v34, v33
	v_div_fmas_f32 v30, v30, v31, v34
	v_add_co_u32_e32 v26, vcc, s4, v4
	v_div_fixup_f32 v16, v30, v16, 1.0
	s_nop 0
	v_addc_co_u32_e32 v27, vcc, 0, v5, vcc
	v_mov_b32_e32 v20, v95
	v_fma_f32 v16, v9, v16, v24
	v_mov_b32_e32 v26, v94
	v_max_f32_e32 v16, 0xda24260, v16
	v_log_f32_e32 v16, v16
	s_waitcnt vmcnt(1)
	v_lshlrev_b32_e32 v28, 16, v20
	v_mul_f32_e32 v20, 0xbfb8aa3b, v28
	v_exp_f32_e32 v20, v20
	s_waitcnt vmcnt(0)
	v_lshlrev_b32_e32 v26, 16, v26
	v_mul_f32_e32 v27, 0x3e000000, v26
	v_add_f32_e32 v16, v15, v16
	v_add_f32_e32 v20, 1.0, v20
	v_div_scale_f32 v30, s[4:5], v20, v20, 1.0
	v_rcp_f32_e32 v31, v30
	s_mov_b32 s4, 0xc000
	v_fma_f32 v33, -v30, v31, 1.0
	v_fmac_f32_e32 v31, v33, v31
	v_div_scale_f32 v33, vcc, 1.0, v20, 1.0
	v_mul_f32_e32 v34, v33, v31
	v_fma_f32 v35, -v30, v34, v33
	v_fmac_f32_e32 v34, v35, v31
	v_fma_f32 v30, -v30, v34, v33
	v_div_fmas_f32 v30, v30, v31, v34
	v_div_fixup_f32 v20, v30, v20, 1.0
	v_add_co_u32_e32 v30, vcc, s4, v4
	v_fma_f32 v20, v9, v20, v24
	s_nop 0
	v_addc_co_u32_e32 v31, vcc, 0, v5, vcc
	v_mov_b32_e32 v26, v97
	v_max_f32_e32 v20, 0xda24260, v20
	v_mov_b32_e32 v30, v96
	v_log_f32_e32 v20, v20
	s_waitcnt vmcnt(1)
	v_lshlrev_b32_e32 v33, 16, v26
	v_mul_f32_e32 v26, 0xbfb8aa3b, v33
	v_exp_f32_e32 v26, v26
	s_waitcnt vmcnt(0)
	v_lshlrev_b32_e32 v30, 16, v30
	v_mul_f32_e32 v30, 0x3e000000, v30
	v_add_f32_e32 v20, v16, v20
	v_add_f32_e32 v26, 1.0, v26
	v_div_scale_f32 v34, s[4:5], v26, v26, 1.0
	v_rcp_f32_e32 v35, v34
	s_mov_b32 s4, 0xd000
	v_fma_f32 v36, -v34, v35, 1.0
	v_fmac_f32_e32 v35, v36, v35
	v_div_scale_f32 v36, vcc, 1.0, v26, 1.0
	v_mul_f32_e32 v37, v36, v35
	v_fma_f32 v38, -v34, v37, v36
	v_fmac_f32_e32 v37, v38, v35
	v_fma_f32 v34, -v34, v37, v36
	v_div_fmas_f32 v34, v34, v35, v37
	v_div_fixup_f32 v26, v34, v26, 1.0
	v_add_u32_e32 v34, 0x8800, v2
	ds_write2_b32 v34, v27, v30 offset0:6 offset1:71
	v_add_co_u32_e32 v30, vcc, s4, v4
	v_fma_f32 v26, v9, v26, v24
	s_nop 0
	v_addc_co_u32_e32 v31, vcc, 0, v5, vcc
	v_mov_b32_e32 v27, v99
	v_max_f32_e32 v26, 0xda24260, v26
	v_mov_b32_e32 v30, v98
	v_log_f32_e32 v26, v26
	s_waitcnt vmcnt(1)
	v_lshlrev_b32_e32 v35, 16, v27
	v_mul_f32_e32 v27, 0xbfb8aa3b, v35
	v_exp_f32_e32 v27, v27
	s_waitcnt vmcnt(0)
	v_lshlrev_b32_e32 v30, 16, v30
	v_mul_f32_e32 v31, 0x3e000000, v30
	v_add_f32_e32 v26, v20, v26
	v_add_f32_e32 v27, 1.0, v27
	v_div_scale_f32 v36, s[4:5], v27, v27, 1.0
	v_rcp_f32_e32 v37, v36
	s_mov_b32 s4, 0xf000
	v_fma_f32 v38, -v36, v37, 1.0
	v_fmac_f32_e32 v37, v38, v37
	v_div_scale_f32 v38, vcc, 1.0, v27, 1.0
	v_mul_f32_e32 v39, v38, v37
	v_fma_f32 v40, -v36, v39, v38
	v_fmac_f32_e32 v39, v40, v37
	v_fma_f32 v36, -v36, v39, v38
	v_div_fmas_f32 v36, v36, v37, v39
	v_add_co_u32_e32 v38, vcc, s4, v4
	v_div_fixup_f32 v27, v36, v27, 1.0
	s_nop 0
	v_addc_co_u32_e32 v39, vcc, 0, v5, vcc
	v_mov_b32_e32 v30, v101
	v_fma_f32 v27, v9, v27, v24
	v_max_f32_e32 v27, 0xda24260, v27
	v_log_f32_e32 v27, v27
	s_waitcnt vmcnt(0)
	v_lshlrev_b32_e32 v37, 16, v30
	v_mul_f32_e32 v30, 0xbfb8aa3b, v37
	v_exp_f32_e32 v30, v30
	v_add_f32_e32 v27, v26, v27
	v_add_f32_e32 v30, 1.0, v30
	v_div_scale_f32 v36, s[4:5], v30, v30, 1.0
	v_rcp_f32_e32 v40, v36
	s_mov_b32 s4, 0x10000
	v_fma_f32 v41, -v36, v40, 1.0
	v_fmac_f32_e32 v40, v41, v40
	v_div_scale_f32 v41, vcc, 1.0, v30, 1.0
	v_mul_f32_e32 v42, v41, v40
	v_fma_f32 v43, -v36, v42, v41
	v_fmac_f32_e32 v42, v43, v40
	v_fma_f32 v36, -v36, v42, v41
	v_div_fmas_f32 v36, v36, v40, v42
	v_div_fixup_f32 v30, v36, v30, 1.0
	v_mov_b32_e32 v36, v100
	v_add_co_u32_e32 v40, vcc, s4, v4
	v_fma_f32 v30, v9, v30, v24
	s_nop 0
	v_addc_co_u32_e32 v41, vcc, 0, v5, vcc
	v_max_f32_e32 v30, 0xda24260, v30
	v_log_f32_e32 v30, v30
	s_waitcnt vmcnt(0)
	v_lshlrev_b32_e32 v36, 16, v36
	v_mul_f32_e32 v36, 0x3e000000, v36
	ds_write2_b32 v34, v31, v36 offset0:136 offset1:201
	v_mov_b32_e32 v31, v103
	v_add_f32_e32 v30, v27, v30
	s_waitcnt vmcnt(0)
	v_lshlrev_b32_e32 v39, 16, v31
	v_mul_f32_e32 v31, 0xbfb8aa3b, v39
	v_exp_f32_e32 v31, v31
	s_nop 0
	v_add_f32_e32 v31, 1.0, v31
	v_div_scale_f32 v34, s[4:5], v31, v31, 1.0
	v_rcp_f32_e32 v36, v34
	s_mov_b32 s4, 0x12000
	v_fma_f32 v38, -v34, v36, 1.0
	v_fmac_f32_e32 v36, v38, v36
	v_div_scale_f32 v38, vcc, 1.0, v31, 1.0
	v_mul_f32_e32 v42, v38, v36
	v_fma_f32 v43, -v34, v42, v38
	v_fmac_f32_e32 v42, v43, v36
	v_fma_f32 v34, -v34, v42, v38
	v_div_fmas_f32 v34, v34, v36, v42
	v_div_fixup_f32 v31, v34, v31, 1.0
	v_mov_b32_e32 v34, v102
	v_add_co_u32_e32 v42, vcc, s4, v4
	v_fma_f32 v31, v9, v31, v24
	s_nop 0
	v_addc_co_u32_e32 v43, vcc, 0, v5, vcc
	v_max_f32_e32 v31, 0xda24260, v31
	v_log_f32_e32 v31, v31
	s_waitcnt vmcnt(0)
	v_lshlrev_b32_e32 v34, 16, v34
	v_mul_f32_e32 v36, 0x3e000000, v34
	v_mov_b32_e32 v34, v105
	v_add_f32_e32 v31, v30, v31
	s_waitcnt vmcnt(0)
	v_lshlrev_b32_e32 v40, 16, v34
	v_mul_f32_e32 v34, 0xbfb8aa3b, v40
	v_exp_f32_e32 v34, v34
	s_nop 0
	v_add_f32_e32 v34, 1.0, v34
	v_div_scale_f32 v38, s[4:5], v34, v34, 1.0
	v_rcp_f32_e32 v41, v38
	s_mov_b32 s4, 0x13000
	v_fma_f32 v44, -v38, v41, 1.0
	v_fmac_f32_e32 v41, v44, v41
	v_div_scale_f32 v44, vcc, 1.0, v34, 1.0
	v_mul_f32_e32 v45, v44, v41
	v_fma_f32 v46, -v38, v45, v44
	v_fmac_f32_e32 v45, v46, v41
	v_fma_f32 v38, -v38, v45, v44
	v_div_fmas_f32 v38, v38, v41, v45
	v_div_fixup_f32 v34, v38, v34, 1.0
	v_mov_b32_e32 v38, v104
	v_add_co_u32_e32 v42, vcc, s4, v4
	v_add_u32_e32 v46, 0x8c00, v2
	s_nop 0
	v_addc_co_u32_e32 v43, vcc, 0, v5, vcc
	v_fma_f32 v34, v9, v34, v24
	v_max_f32_e32 v34, 0xda24260, v34
	v_log_f32_e32 v34, v34
	s_waitcnt vmcnt(0)
	v_lshlrev_b32_e32 v38, 16, v38
	v_mul_f32_e32 v38, 0x3e000000, v38
	ds_write2_b32 v46, v36, v38 offset0:10 offset1:75
	v_mov_b32_e32 v36, v107
	v_add_f32_e32 v34, v31, v34
	s_waitcnt vmcnt(0)
	v_lshlrev_b32_e32 v41, 16, v36
	v_mul_f32_e32 v36, 0xbfb8aa3b, v41
	v_exp_f32_e32 v36, v36
	s_nop 0
	v_add_f32_e32 v36, 1.0, v36
	v_div_scale_f32 v38, s[4:5], v36, v36, 1.0
	v_rcp_f32_e32 v44, v38
	s_mov_b32 s4, 0x15000
	v_fma_f32 v45, -v38, v44, 1.0
	v_fmac_f32_e32 v44, v45, v44
	v_div_scale_f32 v45, vcc, 1.0, v36, 1.0
	v_mul_f32_e32 v47, v45, v44
	v_fma_f32 v48, -v38, v47, v45
	v_fmac_f32_e32 v47, v48, v44
	v_fma_f32 v38, -v38, v47, v45
	v_div_fmas_f32 v38, v38, v44, v47
	v_div_fixup_f32 v36, v38, v36, 1.0
	v_mov_b32_e32 v38, v106
	v_add_co_u32_e32 v44, vcc, s4, v4
	v_fma_f32 v36, v9, v36, v24
	s_nop 0
	v_addc_co_u32_e32 v45, vcc, 0, v5, vcc
	v_max_f32_e32 v36, 0xda24260, v36
	v_log_f32_e32 v36, v36
	s_waitcnt vmcnt(0)
	v_lshlrev_b32_e32 v38, 16, v38
	v_mul_f32_e32 v43, 0x3e000000, v38
	v_mov_b32_e32 v38, v109
	v_add_f32_e32 v36, v34, v36
	v_mov_b32_e32 v44, v108
	s_waitcnt vmcnt(1)
	v_lshlrev_b32_e32 v42, 16, v38
	v_mul_f32_e32 v38, 0xbfb8aa3b, v42
	v_exp_f32_e32 v38, v38
	s_waitcnt vmcnt(0)
	v_lshlrev_b32_e32 v44, 16, v44
	v_mul_f32_e32 v44, 0x3e000000, v44
	ds_write2_b32 v46, v43, v44 offset0:140 offset1:205
	v_add_f32_e32 v38, 1.0, v38
	v_div_scale_f32 v47, s[4:5], v38, v38, 1.0
	v_rcp_f32_e32 v48, v47
	s_mov_b32 s4, 0x16000
	v_fma_f32 v49, -v47, v48, 1.0
	v_fmac_f32_e32 v48, v49, v48
	v_div_scale_f32 v49, vcc, 1.0, v38, 1.0
	v_mul_f32_e32 v50, v49, v48
	v_fma_f32 v51, -v47, v50, v49
	v_fmac_f32_e32 v50, v51, v48
	v_fma_f32 v47, -v47, v50, v49
	v_div_fmas_f32 v47, v47, v48, v50
	v_add_co_u32_e32 v44, vcc, s4, v4
	v_div_fixup_f32 v38, v47, v38, 1.0
	s_nop 0
	v_addc_co_u32_e32 v45, vcc, 0, v5, vcc
	v_mov_b32_e32 v4, v111
	v_fma_f32 v38, v9, v38, v24
	v_max_f32_e32 v38, 0xda24260, v38
	v_log_f32_e32 v38, v38
	s_waitcnt vmcnt(0)
	v_lshlrev_b32_e32 v5, 16, v4
	v_mul_f32_e32 v4, 0xbfb8aa3b, v5
	v_exp_f32_e32 v4, v4
	v_add_f32_e32 v38, v36, v38
	v_add_f32_e32 v4, 1.0, v4
	v_div_scale_f32 v43, s[4:5], v4, v4, 1.0
	v_rcp_f32_e32 v46, v43
	s_nop 0
	v_fma_f32 v47, -v43, v46, 1.0
	v_fmac_f32_e32 v46, v47, v46
	v_div_scale_f32 v47, vcc, 1.0, v4, 1.0
	v_mul_f32_e32 v48, v47, v46
	v_fma_f32 v49, -v43, v48, v47
	v_fmac_f32_e32 v48, v49, v46
	v_fma_f32 v43, -v43, v48, v47
	v_div_fmas_f32 v43, v43, v46, v48
	v_div_fixup_f32 v4, v43, v4, 1.0
	v_fmac_f32_e32 v24, v9, v4
	v_max_f32_e32 v4, 0xda24260, v24
	v_mov_b32_e32 v24, v110
	v_log_f32_e32 v4, v4
	v_cmp_lt_i32_e32 vcc, 0, v29
	v_add_f32_e32 v4, v38, v4
	s_waitcnt vmcnt(0)
	v_lshlrev_b32_e32 v24, 16, v24
	v_mul_f32_e32 v24, 0x3e000000, v24
	ds_write_b32 v2, v24 offset:36920
	v_lshlrev_b32_e32 v2, 2, v32
	ds_write_b32 v2, v4 offset:49920
	s_waitcnt lgkmcnt(0)
	s_barrier
	s_and_saveexec_b64 s[4:5], vcc
	s_cbranch_execnz .LBB0_238
	s_or_b64 exec, exec, s[4:5]
	v_cmp_lt_i32_e32 vcc, 1, v29
	s_and_saveexec_b64 s[4:5], vcc
	s_cbranch_execnz .LBB0_239
